# fp8 GEMM loop exit: dropped the redundant s_nop 15 (s_nop 7 plus the following instructions still cover the MFMA result latency)
# baseline (speedup 1.0000x reference)
; #define PG8_BAR __builtin_amdgcn_s_barrier()
; template <class Epi, class Sched, bool ALIGN_EPI = false, bool SP2 = false, bool F8 = false, bool GATHER = false>
; __device__ __forceinline__ void gemm_phase(PG8_LAS unsigned char* lds, const Gemm g, const Sched& S, const Epi& E, const int tid_in) {
;     ...
;         if constexpr (F8) asm volatile("s_nop 15\n\ts_nop 7" ::: "memory");
;         if constexpr (ALIGN_EPI) { if (wr == 0) PG8_BAR; }
.LBB0_1016:
	s_nop 7
	s_and_b64 vcc, exec, s[50:51]
	s_cbranch_vccz .LBB0_1018
	s_barrier

; #define PG8_BAR __builtin_amdgcn_s_barrier()
; template <class Epi, class Sched, bool ALIGN_EPI = false, bool SP2 = false, bool F8 = false, bool GATHER = false>
; __device__ __forceinline__ void gemm_phase(PG8_LAS unsigned char* lds, const Gemm g, const Sched& S, const Epi& E, const int tid_in) {
;     ...
;         if constexpr (F8) asm volatile("s_nop 15\n\ts_nop 7" ::: "memory");
;         if constexpr (ALIGN_EPI) { if (wr == 0) PG8_BAR; }
.LBB0_1122:
	s_nop 7
	s_mov_b32 s66, s27
	s_mov_b32 s67, s24
	s_and_b64 vcc, exec, s[8:9]
	s_cbranch_vccz .LBB0_1124
	s_barrier
